# MoBA block-loop register copies use v_pk_mov_b32 (half the instructions)
# speedup vs baseline: 1.0960x; 1.0023x over previous
;     ...
; #pragma unroll
;           for (int a = 0; a < 2; ++a)
; #pragma unroll
;             for (int ks = 0; ks < 8; ++ks) vf[a][ks] = vn[a][ks];
.LBB0_622:
	s_mov_b32 s17, s56
	s_waitcnt vmcnt(8)
	v_pk_mov_b32 v[68:69], v[64:65], v[64:65] op_sel:[0,1]
	v_pk_mov_b32 v[70:71], v[66:67], v[66:67] op_sel:[0,1]
	v_pk_mov_b32 v[72:73], v[60:61], v[60:61] op_sel:[0,1]
	v_pk_mov_b32 v[74:75], v[62:63], v[62:63] op_sel:[0,1]
	v_pk_mov_b32 v[76:77], v[56:57], v[56:57] op_sel:[0,1]
	v_pk_mov_b32 v[78:79], v[58:59], v[58:59] op_sel:[0,1]
	v_pk_mov_b32 v[80:81], v[52:53], v[52:53] op_sel:[0,1]
	v_pk_mov_b32 v[82:83], v[54:55], v[54:55] op_sel:[0,1]
	v_pk_mov_b32 v[84:85], v[48:49], v[48:49] op_sel:[0,1]
	v_pk_mov_b32 v[86:87], v[50:51], v[50:51] op_sel:[0,1]
	v_pk_mov_b32 v[88:89], v[44:45], v[44:45] op_sel:[0,1]
	v_pk_mov_b32 v[90:91], v[46:47], v[46:47] op_sel:[0,1]
	v_pk_mov_b32 v[92:93], v[40:41], v[40:41] op_sel:[0,1]
	v_pk_mov_b32 v[94:95], v[42:43], v[42:43] op_sel:[0,1]
	v_pk_mov_b32 v[96:97], v[32:33], v[32:33] op_sel:[0,1]
	v_pk_mov_b32 v[98:99], v[34:35], v[34:35] op_sel:[0,1]
	s_waitcnt vmcnt(7)
	v_pk_mov_b32 v[100:101], v[36:37], v[36:37] op_sel:[0,1]
	v_pk_mov_b32 v[102:103], v[38:39], v[38:39] op_sel:[0,1]
	s_waitcnt vmcnt(6)
	v_pk_mov_b32 v[104:105], v[28:29], v[28:29] op_sel:[0,1]
	v_pk_mov_b32 v[106:107], v[30:31], v[30:31] op_sel:[0,1]
	s_waitcnt vmcnt(5)
	v_pk_mov_b32 v[108:109], v[24:25], v[24:25] op_sel:[0,1]
	v_pk_mov_b32 v[110:111], v[26:27], v[26:27] op_sel:[0,1]
	s_waitcnt vmcnt(4)
	v_pk_mov_b32 v[112:113], v[20:21], v[20:21] op_sel:[0,1]
	v_pk_mov_b32 v[114:115], v[22:23], v[22:23] op_sel:[0,1]
	s_waitcnt vmcnt(3)
	v_pk_mov_b32 v[116:117], v[16:17], v[16:17] op_sel:[0,1]
	v_pk_mov_b32 v[118:119], v[18:19], v[18:19] op_sel:[0,1]
	s_waitcnt vmcnt(2)
	v_pk_mov_b32 v[120:121], v[12:13], v[12:13] op_sel:[0,1]
	v_pk_mov_b32 v[122:123], v[14:15], v[14:15] op_sel:[0,1]
	s_waitcnt vmcnt(1)
	v_pk_mov_b32 v[124:125], v[8:9], v[8:9] op_sel:[0,1]
	v_pk_mov_b32 v[126:127], v[10:11], v[10:11] op_sel:[0,1]
	s_waitcnt vmcnt(0)
	v_pk_mov_b32 v[128:129], v[4:5], v[4:5] op_sel:[0,1]
	v_pk_mov_b32 v[130:131], v[6:7], v[6:7] op_sel:[0,1]
	s_branch .LBB0_592

;     ...
; #pragma unroll
;           for (int a = 0; a < 4; ++a) { kf[a][0] = kn[a][0]; kf[a][1] = kn[a][1]; }
.LBB0_662:
	s_addk_i32 s14, 0x100
	s_cmp_eq_u32 s16, s18
	s_cbranch_scc1 .LBB0_665
	s_mov_b32 s19, s16
	s_waitcnt vmcnt(7)
	v_pk_mov_b32 v[34:35], v[30:31], v[30:31] op_sel:[0,1]
	v_pk_mov_b32 v[36:37], v[32:33], v[32:33] op_sel:[0,1]
	s_waitcnt vmcnt(6)
	v_pk_mov_b32 v[38:39], v[26:27], v[26:27] op_sel:[0,1]
	v_pk_mov_b32 v[40:41], v[28:29], v[28:29] op_sel:[0,1]
	s_waitcnt vmcnt(5)
	v_pk_mov_b32 v[42:43], v[22:23], v[22:23] op_sel:[0,1]
	v_pk_mov_b32 v[44:45], v[24:25], v[24:25] op_sel:[0,1]
	s_waitcnt vmcnt(4)
	v_pk_mov_b32 v[46:47], v[18:19], v[18:19] op_sel:[0,1]
	v_pk_mov_b32 v[48:49], v[20:21], v[20:21] op_sel:[0,1]
	s_waitcnt vmcnt(3)
	v_pk_mov_b32 v[50:51], v[14:15], v[14:15] op_sel:[0,1]
	v_pk_mov_b32 v[52:53], v[16:17], v[16:17] op_sel:[0,1]
	s_waitcnt vmcnt(2)
	v_pk_mov_b32 v[54:55], v[10:11], v[10:11] op_sel:[0,1]
	v_pk_mov_b32 v[56:57], v[12:13], v[12:13] op_sel:[0,1]
	s_waitcnt vmcnt(1)
	v_pk_mov_b32 v[58:59], v[6:7], v[6:7] op_sel:[0,1]
	v_pk_mov_b32 v[60:61], v[8:9], v[8:9] op_sel:[0,1]
	s_waitcnt vmcnt(0)
	v_pk_mov_b32 v[62:63], v[2:3], v[2:3] op_sel:[0,1]
	v_pk_mov_b32 v[64:65], v[4:5], v[4:5] op_sel:[0,1]
	s_branch .LBB0_654
